# P2 big GEMM: per-register decoupled global-load/LDS-write pipeline (saddr loads issued right after each staging reg is written to LDS) + swizzle
# speedup vs baseline: 1.0149x; 1.0036x over previous
.LBB0_465:
	s_mul_hi_i32 s4, s20, 0x38e38e39
	s_lshr_b32 s6, s4, 31
	s_ashr_i32 s4, s4, 4
	s_add_i32 s4, s4, s6
	s_mul_i32 s6, s4, 0x48
	s_sub_i32 s6, s20, s6
	s_lshl_b32 s6, s6, 8
	v_add_u32_e32 v2, s6, v204
	v_ashrrev_i32_e32 v3, 31, v2
	v_lshlrev_b64 v[2:3], 11, v[2:3]
	v_lshl_add_u64 v[168:169], v[162:163], 0, v[2:3]
	v_add_co_u32_e32 v56, vcc, s34, v168
	s_lshl_b32 s7, s4, 8
	s_nop 0
	v_addc_co_u32_e32 v57, vcc, 0, v169, vcc
	v_add_u32_e32 v2, s7, v204
	s_waitcnt vmcnt(9)
	v_add_co_u32_e32 v58, vcc, s35, v168
	v_ashrrev_i32_e32 v3, 31, v2
	s_nop 0
	v_addc_co_u32_e32 v59, vcc, 0, v169, vcc
	v_lshlrev_b64 v[2:3], 11, v[2:3]
	v_add_co_u32_e32 v60, vcc, s36, v168
	v_lshl_add_u64 v[170:171], v[164:165], 0, v[2:3]
	s_nop 0
	v_addc_co_u32_e32 v61, vcc, 0, v169, vcc
	s_waitcnt vmcnt(8)
	v_add_co_u32_e32 v62, vcc, s35, v170
	global_load_dwordx4 v[24:27], v[56:57], off
	global_load_dwordx4 v[28:31], v[58:59], off
	v_addc_co_u32_e32 v63, vcc, 0, v171, vcc
	v_add_co_u32_e32 v64, vcc, s36, v170
	global_load_dwordx4 v[32:35], v[168:169], off
	global_load_dwordx4 v[36:39], v[170:171], off
	v_addc_co_u32_e32 v65, vcc, 0, v171, vcc
	v_add_co_u32_e32 v66, vcc, s34, v170
	global_load_dwordx4 v[40:43], v[62:63], off
	global_load_dwordx4 v[44:47], v[64:65], off
	v_addc_co_u32_e32 v67, vcc, 0, v171, vcc
	global_load_dwordx4 v[48:51], v[60:61], off
	global_load_dwordx4 v[52:55], v[66:67], off
	s_barrier
	global_load_dwordx4 v[114:117], v[168:169], off offset:128
	global_load_dwordx4 v[106:109], v[56:57], off offset:128
	global_load_dwordx4 v[110:113], v[58:59], off offset:128
	global_load_dwordx4 v[126:129], v[60:61], off offset:128
	global_load_dwordx4 v[122:125], v[170:171], off offset:128
	global_load_dwordx4 v[118:121], v[66:67], off offset:128
	global_load_dwordx4 v[134:137], v[62:63], off offset:128
	global_load_dwordx4 v[130:133], v[64:65], off offset:128
	v_subrev_u32_e32 v168, s18, v168
	v_subrev_u32_e32 v170, s16, v170
	v_mov_b32_e32 v2, 0
	s_mov_b32 s4, 0
	v_mov_b32_e32 v3, v2
	v_mov_b32_e32 v4, v2
	v_mov_b32_e32 v5, v2
	v_mov_b32_e32 v6, v2
	v_mov_b32_e32 v7, v2
	v_mov_b32_e32 v8, v2
	v_mov_b32_e32 v9, v2
	v_mov_b32_e32 v10, v2
	v_mov_b32_e32 v11, v2
	v_mov_b32_e32 v12, v2
	v_mov_b32_e32 v13, v2
	v_mov_b32_e32 v14, v2
	v_mov_b32_e32 v15, v2
	v_mov_b32_e32 v16, v2
	v_mov_b32_e32 v17, v2
	v_mov_b32_e32 v18, v2
	v_mov_b32_e32 v19, v2
	v_mov_b32_e32 v20, v2
	v_mov_b32_e32 v21, v2
	v_mov_b32_e32 v22, v2
	v_mov_b32_e32 v23, v2
	v_mov_b32_e32 v56, v2
	v_mov_b32_e32 v57, v2
	v_mov_b32_e32 v58, v2
	v_mov_b32_e32 v59, v2
	v_mov_b32_e32 v60, v2
	v_mov_b32_e32 v61, v2
	v_mov_b32_e32 v62, v2
	v_mov_b32_e32 v63, v2
	v_mov_b32_e32 v64, v2
	v_mov_b32_e32 v65, v2
	v_mov_b32_e32 v66, v2
	v_mov_b32_e32 v67, v2
	v_mov_b32_e32 v68, v2
	v_mov_b32_e32 v69, v2
	v_mov_b32_e32 v70, v2
	v_mov_b32_e32 v71, v2
	v_mov_b32_e32 v72, v2
	v_mov_b32_e32 v73, v2
	v_mov_b32_e32 v74, v2
	v_mov_b32_e32 v75, v2
	v_mov_b32_e32 v76, v2
	v_mov_b32_e32 v77, v2
	v_mov_b32_e32 v78, v2
	v_mov_b32_e32 v79, v2
	v_mov_b32_e32 v80, v2
	v_mov_b32_e32 v81, v2
	v_mov_b32_e32 v82, v2
	v_mov_b32_e32 v83, v2
	v_mov_b32_e32 v84, v2
	v_mov_b32_e32 v85, v2
	s_waitcnt vmcnt(11)
	ds_write_b128 v166, v[40:43] offset:49152
	s_waitcnt vmcnt(10)
	ds_write_b128 v166, v[44:47] offset:57344
	ds_write_b128 v166, v[32:35]
	ds_write_b128 v166, v[36:39] offset:32768
	ds_write_b128 v166, v[24:27] offset:8192
	ds_write_b128 v166, v[28:31] offset:16384
	s_waitcnt vmcnt(9)
	ds_write_b128 v166, v[48:51] offset:24576
	s_waitcnt vmcnt(8)
	ds_write_b128 v166, v[52:55] offset:40960
	v_mov_b32_e32 v24, v2
	v_mov_b32_e32 v25, v2
	v_mov_b32_e32 v26, v2
	v_mov_b32_e32 v27, v2
	v_mov_b32_e32 v28, v2
	v_mov_b32_e32 v29, v2
	v_mov_b32_e32 v30, v2
	v_mov_b32_e32 v31, v2
	v_mov_b32_e32 v32, v2
	v_mov_b32_e32 v33, v2
	v_mov_b32_e32 v34, v2
	v_mov_b32_e32 v35, v2
	v_mov_b32_e32 v36, v2
	v_mov_b32_e32 v37, v2
	v_mov_b32_e32 v38, v2
	v_mov_b32_e32 v39, v2
	v_mov_b32_e32 v40, v2
	v_mov_b32_e32 v41, v2
	v_mov_b32_e32 v42, v2
	v_mov_b32_e32 v43, v2
	v_mov_b32_e32 v44, v2
	v_mov_b32_e32 v45, v2
	v_mov_b32_e32 v46, v2
	v_mov_b32_e32 v47, v2
	v_mov_b32_e32 v48, v2
	v_mov_b32_e32 v49, v2
	v_mov_b32_e32 v50, v2
	v_mov_b32_e32 v51, v2
	v_mov_b32_e32 v52, v2
	v_mov_b32_e32 v53, v2
	v_mov_b32_e32 v54, v2
	v_mov_b32_e32 v55, v2
	v_mov_b32_e32 v86, v2
	v_mov_b32_e32 v87, v2
	v_mov_b32_e32 v88, v2
	v_mov_b32_e32 v89, v2
	v_mov_b32_e32 v90, v2
	v_mov_b32_e32 v91, v2
	v_mov_b32_e32 v92, v2
	v_mov_b32_e32 v93, v2
	v_mov_b32_e32 v94, v2
	v_mov_b32_e32 v95, v2
	v_mov_b32_e32 v96, v2
	v_mov_b32_e32 v97, v2
	v_mov_b32_e32 v98, v2
	v_mov_b32_e32 v99, v2
	v_mov_b32_e32 v100, v2
	v_mov_b32_e32 v101, v2
	v_mov_b32_e32 v102, v2
	v_mov_b32_e32 v103, v2
	v_mov_b32_e32 v104, v2
	v_mov_b32_e32 v105, v2
	v_mov_b32_e32 v138, v2
	v_mov_b32_e32 v139, v2
	v_mov_b32_e32 v140, v2
	v_mov_b32_e32 v141, v2
	v_mov_b32_e32 v142, v2
	v_mov_b32_e32 v143, v2
	v_mov_b32_e32 v144, v2
	v_mov_b32_e32 v145, v2
	v_mov_b32_e32 v146, v2
	v_mov_b32_e32 v147, v2
	v_mov_b32_e32 v148, v2
	v_mov_b32_e32 v149, v2
	v_mov_b32_e32 v150, v2
	v_mov_b32_e32 v151, v2
	v_mov_b32_e32 v152, v2
	v_mov_b32_e32 v153, v2
	v_mov_b32_e32 v154, v2
	v_mov_b32_e32 v155, v2
	v_mov_b32_e32 v156, v2
	v_mov_b32_e32 v157, v2
	v_mov_b32_e32 v158, v2
	v_mov_b32_e32 v159, v2
	v_mov_b32_e32 v160, v2
	v_mov_b32_e32 v161, v2
	s_waitcnt lgkmcnt(0)
	s_barrier
.LBB0_466:
	s_bitcmp1_b32 s4, 0
	s_cselect_b32 s21, 0x12000, 0
	v_or_b32_e32 v184, s21, v206
	v_add_u32_e32 v185, v184, v0
	v_add_u32_e32 v184, v184, v167
	ds_read_b128 v[210:213], v185
	ds_read_b128 v[214:217], v185 offset:2048
	ds_read_b128 v[218:221], v185 offset:4096
	ds_read_b128 v[222:225], v185 offset:6144
	ds_read_b128 v[226:229], v184 offset:32768
	ds_read_b128 v[230:233], v184 offset:34816
	ds_read_b128 v[234:237], v184 offset:36864
	ds_read_b128 v[238:241], v184 offset:38912
	ds_read_b128 v[242:245], v184 offset:40960
	ds_read_b128 v[246:249], v184 offset:43008
	ds_read_b128 v[198:201], v184 offset:45056
	ds_read_b128 v[184:187], v184 offset:47104
	s_add_i32 s10, s4, 1
	s_bitcmp1_b32 s10, 0
	s_cselect_b32 s23, 0x12000, 0
	s_min_i32 s100, s4, 13
	s_lshl_b32 s100, s100, 7
	s_add_u32 vcc_lo, s18, s100
	s_addc_u32 vcc_hi, s19, 0
	s_add_u32 s100, s16, s100
	s_addc_u32 s101, s17, 0
	s_waitcnt lgkmcnt(7)
	v_mfma_f32_16x16x32_bf16 v[158:161], v[226:229], v[210:213], v[158:161]
	v_mfma_f32_16x16x32_bf16 v[94:97], v[226:229], v[214:217], v[94:97]
	v_mfma_f32_16x16x32_bf16 v[62:65], v[226:229], v[218:221], v[62:65]
	v_mfma_f32_16x16x32_bf16 v[30:33], v[226:229], v[222:225], v[30:33]
	v_add_u32_e32 v226, s23, v166
	s_waitcnt vmcnt(7)
	ds_write_b128 v226, v[114:117]
	s_waitcnt lgkmcnt(7)
	v_mfma_f32_16x16x32_bf16 v[154:157], v[230:233], v[210:213], v[154:157]
	v_mfma_f32_16x16x32_bf16 v[90:93], v[230:233], v[214:217], v[90:93]
	global_load_dwordx4 v[114:117], v168, vcc offset:256
	v_mfma_f32_16x16x32_bf16 v[58:61], v[230:233], v[218:221], v[58:61]
	v_mfma_f32_16x16x32_bf16 v[26:29], v[230:233], v[222:225], v[26:29]
	s_waitcnt vmcnt(7)
	ds_write_b128 v226, v[106:109] offset:8192
	s_waitcnt lgkmcnt(7)
	v_mfma_f32_16x16x32_bf16 v[150:153], v[234:237], v[210:213], v[150:153]
	v_mfma_f32_16x16x32_bf16 v[86:89], v[234:237], v[214:217], v[86:89]
	v_add_u32_e32 v106, s34, v168
	global_load_dwordx4 v[106:109], v106, vcc offset:256
	v_mfma_f32_16x16x32_bf16 v[54:57], v[234:237], v[218:221], v[54:57]
	v_mfma_f32_16x16x32_bf16 v[22:25], v[234:237], v[222:225], v[22:25]
	s_waitcnt vmcnt(7)
	ds_write_b128 v226, v[110:113] offset:16384
	s_waitcnt lgkmcnt(7)
	v_mfma_f32_16x16x32_bf16 v[146:149], v[238:241], v[210:213], v[146:149]
	v_mfma_f32_16x16x32_bf16 v[82:85], v[238:241], v[214:217], v[82:85]
	v_add_u32_e32 v110, s35, v168
	global_load_dwordx4 v[110:113], v110, vcc offset:256
	v_mfma_f32_16x16x32_bf16 v[50:53], v[238:241], v[218:221], v[50:53]
	v_mfma_f32_16x16x32_bf16 v[18:21], v[238:241], v[222:225], v[18:21]
	s_waitcnt vmcnt(7)
	ds_write_b128 v226, v[126:129] offset:24576
	s_waitcnt lgkmcnt(7)
	v_mfma_f32_16x16x32_bf16 v[142:145], v[242:245], v[210:213], v[142:145]
	v_mfma_f32_16x16x32_bf16 v[78:81], v[242:245], v[214:217], v[78:81]
	v_add_u32_e32 v126, s36, v168
	global_load_dwordx4 v[126:129], v126, vcc offset:256
	v_mfma_f32_16x16x32_bf16 v[46:49], v[242:245], v[218:221], v[46:49]
	v_mfma_f32_16x16x32_bf16 v[14:17], v[242:245], v[222:225], v[14:17]
	s_waitcnt vmcnt(7)
	ds_write_b128 v226, v[122:125] offset:32768
	s_waitcnt lgkmcnt(7)
	v_mfma_f32_16x16x32_bf16 v[138:141], v[246:249], v[210:213], v[138:141]
	v_mfma_f32_16x16x32_bf16 v[74:77], v[246:249], v[214:217], v[74:77]
	global_load_dwordx4 v[122:125], v170, s[100:101] offset:256
	v_mfma_f32_16x16x32_bf16 v[42:45], v[246:249], v[218:221], v[42:45]
	v_mfma_f32_16x16x32_bf16 v[10:13], v[246:249], v[222:225], v[10:13]
	s_waitcnt vmcnt(7)
	ds_write_b128 v226, v[118:121] offset:40960
	s_waitcnt lgkmcnt(7)
	v_mfma_f32_16x16x32_bf16 v[102:105], v[198:201], v[210:213], v[102:105]
	v_mfma_f32_16x16x32_bf16 v[70:73], v[198:201], v[214:217], v[70:73]
	v_add_u32_e32 v118, s34, v170
	global_load_dwordx4 v[118:121], v118, s[100:101] offset:256
	v_mfma_f32_16x16x32_bf16 v[38:41], v[198:201], v[218:221], v[38:41]
	v_mfma_f32_16x16x32_bf16 v[6:9], v[198:201], v[222:225], v[6:9]
	s_waitcnt vmcnt(7)
	ds_write_b128 v226, v[134:137] offset:49152
	s_waitcnt lgkmcnt(7)
	v_mfma_f32_16x16x32_bf16 v[98:101], v[184:187], v[210:213], v[98:101]
	v_mfma_f32_16x16x32_bf16 v[66:69], v[184:187], v[214:217], v[66:69]
	v_add_u32_e32 v134, s35, v170
	global_load_dwordx4 v[134:137], v134, s[100:101] offset:256
	v_mfma_f32_16x16x32_bf16 v[34:37], v[184:187], v[218:221], v[34:37]
	v_mfma_f32_16x16x32_bf16 v[2:5], v[184:187], v[222:225], v[2:5]
	s_waitcnt vmcnt(7)
	ds_write_b128 v226, v[130:133] offset:57344
	v_add3_u32 v214, s21, v0, v206
	v_xor_b32_e32 v214, 64, v214
	v_add3_u32 v246, s21, v167, v206
	v_xor_b32_e32 v246, 64, v246
	v_add_u32_e32 v130, s36, v170
	global_load_dwordx4 v[130:133], v130, s[100:101] offset:256
	ds_read_b128 v[184:187], v214
	ds_read_b128 v[198:201], v214 offset:2048
	ds_read_b128 v[210:213], v214 offset:4096
	ds_read_b128 v[218:221], v246 offset:32768
	ds_read_b128 v[214:217], v214 offset:6144
	ds_read_b128 v[222:225], v246 offset:34816
	ds_read_b128 v[226:229], v246 offset:36864
	ds_read_b128 v[230:233], v246 offset:38912
	ds_read_b128 v[234:237], v246 offset:40960
	ds_read_b128 v[238:241], v246 offset:43008
	ds_read_b128 v[242:245], v246 offset:45056
	ds_read_b128 v[246:249], v246 offset:47104
	s_waitcnt lgkmcnt(8)
	v_mfma_f32_16x16x32_bf16 v[158:161], v[218:221], v[184:187], v[158:161]
	v_mfma_f32_16x16x32_bf16 v[94:97], v[218:221], v[198:201], v[94:97]
	v_mfma_f32_16x16x32_bf16 v[62:65], v[218:221], v[210:213], v[62:65]
	s_waitcnt lgkmcnt(7)
	v_mfma_f32_16x16x32_bf16 v[30:33], v[218:221], v[214:217], v[30:33]
	s_waitcnt lgkmcnt(6)
	v_mfma_f32_16x16x32_bf16 v[154:157], v[222:225], v[184:187], v[154:157]
	v_mfma_f32_16x16x32_bf16 v[90:93], v[222:225], v[198:201], v[90:93]
	v_mfma_f32_16x16x32_bf16 v[58:61], v[222:225], v[210:213], v[58:61]
	v_mfma_f32_16x16x32_bf16 v[26:29], v[222:225], v[214:217], v[26:29]
	s_waitcnt lgkmcnt(5)
	v_mfma_f32_16x16x32_bf16 v[150:153], v[226:229], v[184:187], v[150:153]
	v_mfma_f32_16x16x32_bf16 v[86:89], v[226:229], v[198:201], v[86:89]
	v_mfma_f32_16x16x32_bf16 v[54:57], v[226:229], v[210:213], v[54:57]
	v_mfma_f32_16x16x32_bf16 v[22:25], v[226:229], v[214:217], v[22:25]
	s_waitcnt lgkmcnt(4)
	v_mfma_f32_16x16x32_bf16 v[146:149], v[230:233], v[184:187], v[146:149]
	v_mfma_f32_16x16x32_bf16 v[82:85], v[230:233], v[198:201], v[82:85]
	v_mfma_f32_16x16x32_bf16 v[50:53], v[230:233], v[210:213], v[50:53]
	v_mfma_f32_16x16x32_bf16 v[18:21], v[230:233], v[214:217], v[18:21]
	s_waitcnt lgkmcnt(3)
	v_mfma_f32_16x16x32_bf16 v[142:145], v[234:237], v[184:187], v[142:145]
	v_mfma_f32_16x16x32_bf16 v[78:81], v[234:237], v[198:201], v[78:81]
	v_mfma_f32_16x16x32_bf16 v[46:49], v[234:237], v[210:213], v[46:49]
	v_mfma_f32_16x16x32_bf16 v[14:17], v[234:237], v[214:217], v[14:17]
	s_waitcnt lgkmcnt(2)
	v_mfma_f32_16x16x32_bf16 v[138:141], v[238:241], v[184:187], v[138:141]
	v_mfma_f32_16x16x32_bf16 v[74:77], v[238:241], v[198:201], v[74:77]
	v_mfma_f32_16x16x32_bf16 v[42:45], v[238:241], v[210:213], v[42:45]
	v_mfma_f32_16x16x32_bf16 v[10:13], v[238:241], v[214:217], v[10:13]
	s_waitcnt lgkmcnt(1)
	v_mfma_f32_16x16x32_bf16 v[102:105], v[242:245], v[184:187], v[102:105]
	v_mfma_f32_16x16x32_bf16 v[70:73], v[242:245], v[198:201], v[70:73]
	v_mfma_f32_16x16x32_bf16 v[38:41], v[242:245], v[210:213], v[38:41]
	v_mfma_f32_16x16x32_bf16 v[6:9], v[242:245], v[214:217], v[6:9]
	s_waitcnt lgkmcnt(0)
	v_mfma_f32_16x16x32_bf16 v[98:101], v[246:249], v[184:187], v[98:101]
	v_mfma_f32_16x16x32_bf16 v[66:69], v[246:249], v[198:201], v[66:69]
	v_mfma_f32_16x16x32_bf16 v[34:37], v[246:249], v[210:213], v[34:37]
	v_mfma_f32_16x16x32_bf16 v[2:5], v[246:249], v[214:217], v[2:5]
	s_waitcnt lgkmcnt(0)
	s_barrier
	s_cmp_eq_u32 s10, 16
	s_mov_b32 s4, s10
	s_cbranch_scc0 .LBB0_466
	s_waitcnt vmcnt(6)
	v_mul_f32_e32 v109, 0xbfb8aa3b, v158
	v_exp_f32_e32 v109, v109
	s_waitcnt vmcnt(5)
	v_mul_f32_e32 v111, 0xbfb8aa3b, v159
	v_exp_f32_e32 v111, v111
	v_mul_f32_e32 v115, 0xbfb8aa3b, v161
	v_add_f32_e32 v109, 1.0, v109
	v_rcp_f32_e32 v114, v109
	v_add_f32_e32 v109, 1.0, v111
	v_mul_f32_e32 v111, 0xbfb8aa3b, v160
	v_exp_f32_e32 v111, v111
	v_exp_f32_e32 v117, v115
	v_rcp_f32_e32 v116, v109
	s_waitcnt vmcnt(2)
	v_mov_b32_e32 v118, v158
	v_add_f32_e32 v109, 1.0, v111
	v_rcp_f32_e32 v115, v109
	v_add_f32_e32 v109, 1.0, v117
	v_rcp_f32_e32 v117, v109
	v_mov_b32_e32 v119, v160
	v_pk_mul_f32 v[114:115], v[118:119], v[114:115]
	v_mov_b32_e32 v118, v154
	v_mov_b32_e32 v119, v156
	v_mov_b32_e32 v160, v159
	v_pk_mul_f32 v[114:115], v[118:119], v[114:115]
	v_pk_mul_f32 v[116:117], v[160:161], v[116:117]
	v_mov_b32_e32 v156, v155
	v_pk_mul_f32 v[116:117], v[156:157], v[116:117]
	v_and_b32_sdwa v111, v115, v177 dst_sel:DWORD dst_unused:UNUSED_PAD src0_sel:WORD_1 src1_sel:DWORD
	v_and_b32_sdwa v118, v114, v177 dst_sel:DWORD dst_unused:UNUSED_PAD src0_sel:WORD_1 src1_sel:DWORD
	v_add3_u32 v111, v115, v111, s28
	v_and_b32_sdwa v115, v117, v177 dst_sel:DWORD dst_unused:UNUSED_PAD src0_sel:WORD_1 src1_sel:DWORD
	v_add3_u32 v114, v114, v118, s28
	v_and_b32_sdwa v118, v116, v177 dst_sel:DWORD dst_unused:UNUSED_PAD src0_sel:WORD_1 src1_sel:DWORD
	v_add3_u32 v115, v117, v115, s28
	v_or_b32_e32 v106, s7, v207
	v_add3_u32 v116, v116, v118, s28
	v_and_b32_e32 v115, 0xffff0000, v115
	v_ashrrev_i32_e32 v106, 1, v106
	v_and_b32_e32 v116, 0xffff0000, v116
	v_or_b32_sdwa v115, v115, v111 dst_sel:DWORD dst_unused:UNUSED_PAD src0_sel:DWORD src1_sel:WORD_1
	v_mul_f32_e32 v111, 0xbfb8aa3b, v150
	v_or_b32_e32 v108, v106, v208
	v_or_b32_sdwa v114, v116, v114 dst_sel:DWORD dst_unused:UNUSED_PAD src0_sel:DWORD src1_sel:WORD_1
	v_exp_f32_e32 v111, v111
	v_mul_f32_e32 v116, 0xbfb8aa3b, v151
	v_add_u32_e32 v110, s6, v205
	v_mov_b64_e32 v[106:107], s[14:15]
	v_ashrrev_i32_e32 v109, 31, v108
	v_exp_f32_e32 v116, v116
	v_mad_i64_i32 v[112:113], s[6:7], v110, s52, v[106:107]
	v_lshlrev_b64 v[108:109], 1, v[108:109]
	v_lshl_add_u64 v[112:113], v[112:113], 0, v[108:109]
	s_waitcnt vmcnt(0)
	global_store_dwordx2 v[112:113], v[114:115], off
	v_add_f32_e32 v111, 1.0, v111
	v_mul_f32_e32 v115, 0xbfb8aa3b, v152
	v_rcp_f32_e32 v114, v111
	v_add_f32_e32 v111, 1.0, v116
	v_exp_f32_e32 v115, v115
	v_mul_f32_e32 v116, 0xbfb8aa3b, v153
	v_exp_f32_e32 v117, v116
	v_rcp_f32_e32 v116, v111
	v_add_f32_e32 v111, 1.0, v115
	v_rcp_f32_e32 v115, v111
	v_add_f32_e32 v111, 1.0, v117
	v_rcp_f32_e32 v117, v111
	v_mov_b32_e32 v118, v150
	v_mov_b32_e32 v119, v152
	v_pk_mul_f32 v[114:115], v[118:119], v[114:115]
	v_mov_b32_e32 v118, v146
	v_mov_b32_e32 v119, v148
	v_mov_b32_e32 v152, v151
	v_pk_mul_f32 v[114:115], v[118:119], v[114:115]
	v_pk_mul_f32 v[116:117], v[152:153], v[116:117]
	v_mov_b32_e32 v148, v147
	v_pk_mul_f32 v[116:117], v[148:149], v[116:117]
	v_and_b32_sdwa v111, v115, v177 dst_sel:DWORD dst_unused:UNUSED_PAD src0_sel:WORD_1 src1_sel:DWORD
	v_and_b32_sdwa v118, v114, v177 dst_sel:DWORD dst_unused:UNUSED_PAD src0_sel:WORD_1 src1_sel:DWORD
	v_add3_u32 v111, v115, v111, s28
	v_and_b32_sdwa v115, v117, v177 dst_sel:DWORD dst_unused:UNUSED_PAD src0_sel:WORD_1 src1_sel:DWORD
	v_add3_u32 v114, v114, v118, s28
	v_and_b32_sdwa v118, v116, v177 dst_sel:DWORD dst_unused:UNUSED_PAD src0_sel:WORD_1 src1_sel:DWORD
	v_add3_u32 v115, v117, v115, s28
	v_add3_u32 v116, v116, v118, s28
	v_and_b32_e32 v115, 0xffff0000, v115
	v_and_b32_e32 v116, 0xffff0000, v116
	v_or_b32_sdwa v115, v115, v111 dst_sel:DWORD dst_unused:UNUSED_PAD src0_sel:DWORD src1_sel:WORD_1
	v_mul_f32_e32 v111, 0xbfb8aa3b, v142
	v_or_b32_sdwa v114, v116, v114 dst_sel:DWORD dst_unused:UNUSED_PAD src0_sel:DWORD src1_sel:WORD_1
	v_exp_f32_e32 v111, v111
	v_mul_f32_e32 v116, 0xbfb8aa3b, v143
	v_exp_f32_e32 v116, v116
	global_store_dwordx2 v[112:113], v[114:115], off offset:32
	v_add_f32_e32 v111, 1.0, v111
	v_mul_f32_e32 v115, 0xbfb8aa3b, v144
	v_rcp_f32_e32 v114, v111
	v_add_f32_e32 v111, 1.0, v116
	v_exp_f32_e32 v115, v115
	v_mul_f32_e32 v116, 0xbfb8aa3b, v145
	v_exp_f32_e32 v117, v116
	v_rcp_f32_e32 v116, v111
	v_add_f32_e32 v111, 1.0, v115
	v_rcp_f32_e32 v115, v111
	v_add_f32_e32 v111, 1.0, v117
	v_rcp_f32_e32 v117, v111
	v_mov_b32_e32 v118, v142
	v_mov_b32_e32 v119, v144
	v_pk_mul_f32 v[114:115], v[118:119], v[114:115]
	v_mov_b32_e32 v118, v138
	v_mov_b32_e32 v119, v140
	v_mov_b32_e32 v144, v143
	v_pk_mul_f32 v[114:115], v[118:119], v[114:115]
	v_pk_mul_f32 v[116:117], v[144:145], v[116:117]
	v_mov_b32_e32 v140, v139
	v_pk_mul_f32 v[116:117], v[140:141], v[116:117]
	v_and_b32_sdwa v111, v115, v177 dst_sel:DWORD dst_unused:UNUSED_PAD src0_sel:WORD_1 src1_sel:DWORD
	v_and_b32_sdwa v118, v114, v177 dst_sel:DWORD dst_unused:UNUSED_PAD src0_sel:WORD_1 src1_sel:DWORD
	v_add3_u32 v111, v115, v111, s28
	v_and_b32_sdwa v115, v117, v177 dst_sel:DWORD dst_unused:UNUSED_PAD src0_sel:WORD_1 src1_sel:DWORD
	v_add3_u32 v114, v114, v118, s28
	v_and_b32_sdwa v118, v116, v177 dst_sel:DWORD dst_unused:UNUSED_PAD src0_sel:WORD_1 src1_sel:DWORD
	v_add3_u32 v115, v117, v115, s28
	v_add3_u32 v116, v116, v118, s28
	v_and_b32_e32 v115, 0xffff0000, v115
	v_and_b32_e32 v116, 0xffff0000, v116
	v_or_b32_sdwa v115, v115, v111 dst_sel:DWORD dst_unused:UNUSED_PAD src0_sel:DWORD src1_sel:WORD_1
	v_mul_f32_e32 v111, 0xbfb8aa3b, v102
	v_or_b32_sdwa v114, v116, v114 dst_sel:DWORD dst_unused:UNUSED_PAD src0_sel:DWORD src1_sel:WORD_1
	v_exp_f32_e32 v111, v111
	v_mul_f32_e32 v116, 0xbfb8aa3b, v103
	v_exp_f32_e32 v116, v116
	global_store_dwordx2 v[112:113], v[114:115], off offset:64
	v_add_f32_e32 v111, 1.0, v111
	v_mul_f32_e32 v115, 0xbfb8aa3b, v104
	v_rcp_f32_e32 v114, v111
	v_add_f32_e32 v111, 1.0, v116
	v_exp_f32_e32 v115, v115
	v_mul_f32_e32 v116, 0xbfb8aa3b, v105
	v_exp_f32_e32 v117, v116
	v_rcp_f32_e32 v116, v111
	v_add_f32_e32 v111, 1.0, v115
	v_rcp_f32_e32 v115, v111
	v_add_f32_e32 v111, 1.0, v117
	v_rcp_f32_e32 v117, v111
	v_mov_b32_e32 v118, v102
	v_mov_b32_e32 v119, v104
	v_mov_b32_e32 v104, v103
	v_pk_mul_f32 v[114:115], v[118:119], v[114:115]
	v_mov_b32_e32 v119, v100
	v_pk_mul_f32 v[102:103], v[104:105], v[116:117]
	v_mov_b32_e32 v100, v99
	v_mov_b32_e32 v118, v98
	v_pk_mul_f32 v[98:99], v[100:101], v[102:103]
	v_pk_mul_f32 v[114:115], v[118:119], v[114:115]
	v_and_b32_sdwa v102, v99, v177 dst_sel:DWORD dst_unused:UNUSED_PAD src0_sel:WORD_1 src1_sel:DWORD
	v_and_b32_sdwa v103, v98, v177 dst_sel:DWORD dst_unused:UNUSED_PAD src0_sel:WORD_1 src1_sel:DWORD
	v_and_b32_sdwa v100, v115, v177 dst_sel:DWORD dst_unused:UNUSED_PAD src0_sel:WORD_1 src1_sel:DWORD
	v_and_b32_sdwa v101, v114, v177 dst_sel:DWORD dst_unused:UNUSED_PAD src0_sel:WORD_1 src1_sel:DWORD
	v_add3_u32 v99, v99, v102, s28
	v_add3_u32 v98, v98, v103, s28
	v_add3_u32 v101, v114, v101, s28
	v_add3_u32 v100, v115, v100, s28
	v_and_b32_e32 v99, 0xffff0000, v99
	v_and_b32_e32 v98, 0xffff0000, v98
	v_or_b32_sdwa v99, v99, v100 dst_sel:DWORD dst_unused:UNUSED_PAD src0_sel:DWORD src1_sel:WORD_1
	v_or_b32_sdwa v98, v98, v101 dst_sel:DWORD dst_unused:UNUSED_PAD src0_sel:DWORD src1_sel:WORD_1
	global_store_dwordx2 v[112:113], v[98:99], off offset:96
	v_mul_f32_e32 v99, 0xbfb8aa3b, v94
	v_exp_f32_e32 v100, v99
	v_mul_f32_e32 v99, 0xbfb8aa3b, v95
	v_mul_f32_e32 v102, 0xbfb8aa3b, v96
	v_exp_f32_e32 v101, v99
	v_exp_f32_e32 v103, v102
	v_mul_f32_e32 v102, 0xbfb8aa3b, v97
	v_exp_f32_e32 v104, v102
	v_add_f32_e32 v101, 1.0, v101
	v_add_f32_e32 v100, 1.0, v100
	v_rcp_f32_e32 v102, v101
	v_add_f32_e32 v101, 1.0, v103
	v_add_f32_e32 v103, 1.0, v104
	v_rcp_f32_e32 v100, v100
	v_rcp_f32_e32 v101, v101
	v_rcp_f32_e32 v103, v103
	v_mov_b32_e32 v104, v94
	v_mov_b32_e32 v105, v96
	v_mov_b32_e32 v96, v95
	v_pk_mul_f32 v[100:101], v[104:105], v[100:101]
	v_mov_b32_e32 v105, v92
	v_pk_mul_f32 v[94:95], v[96:97], v[102:103]
	v_mov_b32_e32 v92, v91
	v_mov_b32_e32 v104, v90
	v_pk_mul_f32 v[90:91], v[92:93], v[94:95]
	v_pk_mul_f32 v[100:101], v[104:105], v[100:101]
	v_and_b32_sdwa v94, v91, v177 dst_sel:DWORD dst_unused:UNUSED_PAD src0_sel:WORD_1 src1_sel:DWORD
	v_and_b32_sdwa v92, v101, v177 dst_sel:DWORD dst_unused:UNUSED_PAD src0_sel:WORD_1 src1_sel:DWORD
	v_and_b32_sdwa v95, v90, v177 dst_sel:DWORD dst_unused:UNUSED_PAD src0_sel:WORD_1 src1_sel:DWORD
	v_add3_u32 v91, v91, v94, s28
	v_and_b32_sdwa v93, v100, v177 dst_sel:DWORD dst_unused:UNUSED_PAD src0_sel:WORD_1 src1_sel:DWORD
	v_add3_u32 v92, v101, v92, s28
	v_add3_u32 v90, v90, v95, s28
	v_and_b32_e32 v91, 0xffff0000, v91
	v_add3_u32 v93, v100, v93, s28
	v_and_b32_e32 v90, 0xffff0000, v90
	v_or_b32_sdwa v91, v91, v92 dst_sel:DWORD dst_unused:UNUSED_PAD src0_sel:DWORD src1_sel:WORD_1
	v_mul_f32_e32 v92, 0xbfb8aa3b, v86
	v_or_b32_sdwa v90, v90, v93 dst_sel:DWORD dst_unused:UNUSED_PAD src0_sel:DWORD src1_sel:WORD_1
	v_exp_f32_e32 v92, v92
	v_mul_f32_e32 v93, 0xbfb8aa3b, v87
	v_or_b32_e32 v98, 16, v110
	v_exp_f32_e32 v93, v93
	v_mad_i64_i32 v[98:99], s[6:7], v98, s52, v[106:107]
	v_lshl_add_u64 v[98:99], v[98:99], 0, v[108:109]
	global_store_dwordx2 v[98:99], v[90:91], off
	v_add_f32_e32 v90, 1.0, v92
	v_mul_f32_e32 v92, 0xbfb8aa3b, v88
	v_add_f32_e32 v91, 1.0, v93
	v_exp_f32_e32 v93, v92
	v_mul_f32_e32 v92, 0xbfb8aa3b, v89
	v_exp_f32_e32 v94, v92
	v_rcp_f32_e32 v92, v91
	v_add_f32_e32 v91, 1.0, v93
	v_rcp_f32_e32 v90, v90
	v_add_f32_e32 v93, 1.0, v94
	v_rcp_f32_e32 v91, v91
	v_rcp_f32_e32 v93, v93
	v_mov_b32_e32 v94, v86
	v_mov_b32_e32 v95, v88
	v_mov_b32_e32 v88, v87
	v_pk_mul_f32 v[90:91], v[94:95], v[90:91]
	v_mov_b32_e32 v95, v84
	v_pk_mul_f32 v[86:87], v[88:89], v[92:93]
	v_mov_b32_e32 v84, v83
	v_mov_b32_e32 v94, v82
	v_pk_mul_f32 v[82:83], v[84:85], v[86:87]
	v_pk_mul_f32 v[90:91], v[94:95], v[90:91]
	v_and_b32_sdwa v86, v83, v177 dst_sel:DWORD dst_unused:UNUSED_PAD src0_sel:WORD_1 src1_sel:DWORD
	v_and_b32_sdwa v84, v91, v177 dst_sel:DWORD dst_unused:UNUSED_PAD src0_sel:WORD_1 src1_sel:DWORD
	v_and_b32_sdwa v87, v82, v177 dst_sel:DWORD dst_unused:UNUSED_PAD src0_sel:WORD_1 src1_sel:DWORD
	v_add3_u32 v83, v83, v86, s28
	v_and_b32_sdwa v85, v90, v177 dst_sel:DWORD dst_unused:UNUSED_PAD src0_sel:WORD_1 src1_sel:DWORD
	v_add3_u32 v84, v91, v84, s28
	v_add3_u32 v82, v82, v87, s28
	v_and_b32_e32 v83, 0xffff0000, v83
	v_add3_u32 v85, v90, v85, s28
	v_and_b32_e32 v82, 0xffff0000, v82
	v_or_b32_sdwa v83, v83, v84 dst_sel:DWORD dst_unused:UNUSED_PAD src0_sel:DWORD src1_sel:WORD_1
	v_mul_f32_e32 v84, 0xbfb8aa3b, v78
	v_or_b32_sdwa v82, v82, v85 dst_sel:DWORD dst_unused:UNUSED_PAD src0_sel:DWORD src1_sel:WORD_1
	v_exp_f32_e32 v84, v84
	v_mul_f32_e32 v85, 0xbfb8aa3b, v79
	v_exp_f32_e32 v85, v85
	global_store_dwordx2 v[98:99], v[82:83], off offset:32
	v_add_f32_e32 v82, 1.0, v84
	v_mul_f32_e32 v84, 0xbfb8aa3b, v80
	v_add_f32_e32 v83, 1.0, v85
	v_exp_f32_e32 v85, v84
	v_mul_f32_e32 v84, 0xbfb8aa3b, v81
	v_exp_f32_e32 v86, v84
	v_rcp_f32_e32 v84, v83
	v_add_f32_e32 v83, 1.0, v85
	v_rcp_f32_e32 v82, v82
	v_add_f32_e32 v85, 1.0, v86
	v_rcp_f32_e32 v83, v83
	v_rcp_f32_e32 v85, v85
	v_mov_b32_e32 v86, v78
	v_mov_b32_e32 v87, v80
	v_mov_b32_e32 v80, v79
	v_pk_mul_f32 v[82:83], v[86:87], v[82:83]
	v_mov_b32_e32 v87, v76
	v_pk_mul_f32 v[78:79], v[80:81], v[84:85]
	v_mov_b32_e32 v76, v75
	v_mov_b32_e32 v86, v74
	v_pk_mul_f32 v[74:75], v[76:77], v[78:79]
	v_pk_mul_f32 v[82:83], v[86:87], v[82:83]
	v_and_b32_sdwa v78, v75, v177 dst_sel:DWORD dst_unused:UNUSED_PAD src0_sel:WORD_1 src1_sel:DWORD
	v_and_b32_sdwa v76, v83, v177 dst_sel:DWORD dst_unused:UNUSED_PAD src0_sel:WORD_1 src1_sel:DWORD
	v_and_b32_sdwa v79, v74, v177 dst_sel:DWORD dst_unused:UNUSED_PAD src0_sel:WORD_1 src1_sel:DWORD
	v_add3_u32 v75, v75, v78, s28
	v_and_b32_sdwa v77, v82, v177 dst_sel:DWORD dst_unused:UNUSED_PAD src0_sel:WORD_1 src1_sel:DWORD
	v_add3_u32 v76, v83, v76, s28
	v_add3_u32 v74, v74, v79, s28
	v_and_b32_e32 v75, 0xffff0000, v75
	v_add3_u32 v77, v82, v77, s28
	v_and_b32_e32 v74, 0xffff0000, v74
	v_or_b32_sdwa v75, v75, v76 dst_sel:DWORD dst_unused:UNUSED_PAD src0_sel:DWORD src1_sel:WORD_1
	v_mul_f32_e32 v76, 0xbfb8aa3b, v70
	v_or_b32_sdwa v74, v74, v77 dst_sel:DWORD dst_unused:UNUSED_PAD src0_sel:DWORD src1_sel:WORD_1
	v_exp_f32_e32 v76, v76
	v_mul_f32_e32 v77, 0xbfb8aa3b, v71
	v_exp_f32_e32 v77, v77
	global_store_dwordx2 v[98:99], v[74:75], off offset:64
	v_add_f32_e32 v74, 1.0, v76
	v_mul_f32_e32 v76, 0xbfb8aa3b, v72
	v_add_f32_e32 v75, 1.0, v77
	v_exp_f32_e32 v77, v76
	v_mul_f32_e32 v76, 0xbfb8aa3b, v73
	v_exp_f32_e32 v78, v76
	v_rcp_f32_e32 v76, v75
	v_add_f32_e32 v75, 1.0, v77
	v_rcp_f32_e32 v74, v74
	v_add_f32_e32 v77, 1.0, v78
	v_rcp_f32_e32 v75, v75
	v_rcp_f32_e32 v77, v77
	v_mov_b32_e32 v78, v70
	v_mov_b32_e32 v79, v72
	v_mov_b32_e32 v72, v71
	v_pk_mul_f32 v[74:75], v[78:79], v[74:75]
	v_mov_b32_e32 v79, v68
	v_pk_mul_f32 v[70:71], v[72:73], v[76:77]
	v_mov_b32_e32 v68, v67
	v_mov_b32_e32 v78, v66
	v_pk_mul_f32 v[66:67], v[68:69], v[70:71]
	v_pk_mul_f32 v[74:75], v[78:79], v[74:75]
	v_and_b32_sdwa v70, v67, v177 dst_sel:DWORD dst_unused:UNUSED_PAD src0_sel:WORD_1 src1_sel:DWORD
	v_and_b32_sdwa v71, v66, v177 dst_sel:DWORD dst_unused:UNUSED_PAD src0_sel:WORD_1 src1_sel:DWORD
	v_and_b32_sdwa v68, v75, v177 dst_sel:DWORD dst_unused:UNUSED_PAD src0_sel:WORD_1 src1_sel:DWORD
	v_and_b32_sdwa v69, v74, v177 dst_sel:DWORD dst_unused:UNUSED_PAD src0_sel:WORD_1 src1_sel:DWORD
	v_add3_u32 v67, v67, v70, s28
	v_add3_u32 v66, v66, v71, s28
	v_add3_u32 v69, v74, v69, s28
	v_add3_u32 v68, v75, v68, s28
	v_and_b32_e32 v67, 0xffff0000, v67
	v_and_b32_e32 v66, 0xffff0000, v66
	v_or_b32_sdwa v67, v67, v68 dst_sel:DWORD dst_unused:UNUSED_PAD src0_sel:DWORD src1_sel:WORD_1
	v_or_b32_sdwa v66, v66, v69 dst_sel:DWORD dst_unused:UNUSED_PAD src0_sel:DWORD src1_sel:WORD_1
	global_store_dwordx2 v[98:99], v[66:67], off offset:96
	v_mul_f32_e32 v67, 0xbfb8aa3b, v62
	v_exp_f32_e32 v68, v67
	v_mul_f32_e32 v67, 0xbfb8aa3b, v63
	v_mul_f32_e32 v70, 0xbfb8aa3b, v64
	v_exp_f32_e32 v69, v67
	v_exp_f32_e32 v71, v70
	v_mul_f32_e32 v70, 0xbfb8aa3b, v65
	v_exp_f32_e32 v72, v70
	v_add_f32_e32 v69, 1.0, v69
	v_add_f32_e32 v68, 1.0, v68
	v_rcp_f32_e32 v70, v69
	v_add_f32_e32 v69, 1.0, v71
	v_add_f32_e32 v71, 1.0, v72
	v_rcp_f32_e32 v68, v68
	v_rcp_f32_e32 v69, v69
	v_rcp_f32_e32 v71, v71
	v_mov_b32_e32 v72, v62
	v_mov_b32_e32 v73, v64
	v_mov_b32_e32 v64, v63
	v_pk_mul_f32 v[68:69], v[72:73], v[68:69]
	v_mov_b32_e32 v73, v60
	v_pk_mul_f32 v[62:63], v[64:65], v[70:71]
	v_mov_b32_e32 v60, v59
	v_mov_b32_e32 v72, v58
	v_pk_mul_f32 v[58:59], v[60:61], v[62:63]
	v_pk_mul_f32 v[68:69], v[72:73], v[68:69]
	v_and_b32_sdwa v62, v59, v177 dst_sel:DWORD dst_unused:UNUSED_PAD src0_sel:WORD_1 src1_sel:DWORD
	v_and_b32_sdwa v60, v69, v177 dst_sel:DWORD dst_unused:UNUSED_PAD src0_sel:WORD_1 src1_sel:DWORD
	v_and_b32_sdwa v63, v58, v177 dst_sel:DWORD dst_unused:UNUSED_PAD src0_sel:WORD_1 src1_sel:DWORD
	v_add3_u32 v59, v59, v62, s28
	v_and_b32_sdwa v61, v68, v177 dst_sel:DWORD dst_unused:UNUSED_PAD src0_sel:WORD_1 src1_sel:DWORD
	v_add3_u32 v60, v69, v60, s28
	v_add3_u32 v58, v58, v63, s28
	v_and_b32_e32 v59, 0xffff0000, v59
	v_add3_u32 v61, v68, v61, s28
	v_and_b32_e32 v58, 0xffff0000, v58
	v_or_b32_sdwa v59, v59, v60 dst_sel:DWORD dst_unused:UNUSED_PAD src0_sel:DWORD src1_sel:WORD_1
	v_mul_f32_e32 v60, 0xbfb8aa3b, v54
	v_or_b32_sdwa v58, v58, v61 dst_sel:DWORD dst_unused:UNUSED_PAD src0_sel:DWORD src1_sel:WORD_1
	v_exp_f32_e32 v60, v60
	v_mul_f32_e32 v61, 0xbfb8aa3b, v55
	v_or_b32_e32 v66, 32, v110
	v_exp_f32_e32 v61, v61
	v_mad_i64_i32 v[66:67], s[6:7], v66, s52, v[106:107]
	v_lshl_add_u64 v[66:67], v[66:67], 0, v[108:109]
	global_store_dwordx2 v[66:67], v[58:59], off
	v_add_f32_e32 v58, 1.0, v60
	v_mul_f32_e32 v60, 0xbfb8aa3b, v56
	v_add_f32_e32 v59, 1.0, v61
	v_exp_f32_e32 v61, v60
	v_mul_f32_e32 v60, 0xbfb8aa3b, v57
	v_exp_f32_e32 v62, v60
	v_rcp_f32_e32 v60, v59
	v_add_f32_e32 v59, 1.0, v61
	v_rcp_f32_e32 v58, v58
	v_add_f32_e32 v61, 1.0, v62
	v_rcp_f32_e32 v59, v59
	v_rcp_f32_e32 v61, v61
	v_mov_b32_e32 v62, v54
	v_mov_b32_e32 v63, v56
	v_mov_b32_e32 v56, v55
	v_pk_mul_f32 v[58:59], v[62:63], v[58:59]
	v_mov_b32_e32 v63, v52
	v_pk_mul_f32 v[54:55], v[56:57], v[60:61]
	v_mov_b32_e32 v52, v51
	v_mov_b32_e32 v62, v50
	v_pk_mul_f32 v[50:51], v[52:53], v[54:55]
	v_pk_mul_f32 v[58:59], v[62:63], v[58:59]
	v_and_b32_sdwa v54, v51, v177 dst_sel:DWORD dst_unused:UNUSED_PAD src0_sel:WORD_1 src1_sel:DWORD
	v_and_b32_sdwa v52, v59, v177 dst_sel:DWORD dst_unused:UNUSED_PAD src0_sel:WORD_1 src1_sel:DWORD
	v_and_b32_sdwa v55, v50, v177 dst_sel:DWORD dst_unused:UNUSED_PAD src0_sel:WORD_1 src1_sel:DWORD
	v_add3_u32 v51, v51, v54, s28
	v_and_b32_sdwa v53, v58, v177 dst_sel:DWORD dst_unused:UNUSED_PAD src0_sel:WORD_1 src1_sel:DWORD
	v_add3_u32 v52, v59, v52, s28
	v_add3_u32 v50, v50, v55, s28
	v_and_b32_e32 v51, 0xffff0000, v51
	v_add3_u32 v53, v58, v53, s28
	v_and_b32_e32 v50, 0xffff0000, v50
	v_or_b32_sdwa v51, v51, v52 dst_sel:DWORD dst_unused:UNUSED_PAD src0_sel:DWORD src1_sel:WORD_1
	v_mul_f32_e32 v52, 0xbfb8aa3b, v46
	v_or_b32_sdwa v50, v50, v53 dst_sel:DWORD dst_unused:UNUSED_PAD src0_sel:DWORD src1_sel:WORD_1
	v_exp_f32_e32 v52, v52
	v_mul_f32_e32 v53, 0xbfb8aa3b, v47
	v_exp_f32_e32 v53, v53
	global_store_dwordx2 v[66:67], v[50:51], off offset:32
	v_add_f32_e32 v50, 1.0, v52
	v_mul_f32_e32 v52, 0xbfb8aa3b, v48
	v_add_f32_e32 v51, 1.0, v53
	v_exp_f32_e32 v53, v52
	v_mul_f32_e32 v52, 0xbfb8aa3b, v49
	v_exp_f32_e32 v54, v52
	v_rcp_f32_e32 v52, v51
	v_add_f32_e32 v51, 1.0, v53
	v_rcp_f32_e32 v50, v50
	v_add_f32_e32 v53, 1.0, v54
	v_rcp_f32_e32 v51, v51
	v_rcp_f32_e32 v53, v53
	v_mov_b32_e32 v54, v46
	v_mov_b32_e32 v55, v48
	v_mov_b32_e32 v48, v47
	v_pk_mul_f32 v[50:51], v[54:55], v[50:51]
	v_mov_b32_e32 v55, v44
	v_pk_mul_f32 v[46:47], v[48:49], v[52:53]
	v_mov_b32_e32 v44, v43
	v_mov_b32_e32 v54, v42
	v_pk_mul_f32 v[42:43], v[44:45], v[46:47]
	v_pk_mul_f32 v[50:51], v[54:55], v[50:51]
	v_and_b32_sdwa v46, v43, v177 dst_sel:DWORD dst_unused:UNUSED_PAD src0_sel:WORD_1 src1_sel:DWORD
	v_and_b32_sdwa v44, v51, v177 dst_sel:DWORD dst_unused:UNUSED_PAD src0_sel:WORD_1 src1_sel:DWORD
	v_and_b32_sdwa v47, v42, v177 dst_sel:DWORD dst_unused:UNUSED_PAD src0_sel:WORD_1 src1_sel:DWORD
	v_add3_u32 v43, v43, v46, s28
	v_and_b32_sdwa v45, v50, v177 dst_sel:DWORD dst_unused:UNUSED_PAD src0_sel:WORD_1 src1_sel:DWORD
	v_add3_u32 v44, v51, v44, s28
	v_add3_u32 v42, v42, v47, s28
	v_and_b32_e32 v43, 0xffff0000, v43
	v_add3_u32 v45, v50, v45, s28
	v_and_b32_e32 v42, 0xffff0000, v42
	v_or_b32_sdwa v43, v43, v44 dst_sel:DWORD dst_unused:UNUSED_PAD src0_sel:DWORD src1_sel:WORD_1
	v_mul_f32_e32 v44, 0xbfb8aa3b, v38
	v_or_b32_sdwa v42, v42, v45 dst_sel:DWORD dst_unused:UNUSED_PAD src0_sel:DWORD src1_sel:WORD_1
	v_exp_f32_e32 v44, v44
	v_mul_f32_e32 v45, 0xbfb8aa3b, v39
	v_exp_f32_e32 v45, v45
	global_store_dwordx2 v[66:67], v[42:43], off offset:64
	v_add_f32_e32 v42, 1.0, v44
	v_mul_f32_e32 v44, 0xbfb8aa3b, v40
	v_add_f32_e32 v43, 1.0, v45
	v_exp_f32_e32 v45, v44
	v_mul_f32_e32 v44, 0xbfb8aa3b, v41
	v_exp_f32_e32 v46, v44
	v_rcp_f32_e32 v44, v43
	v_add_f32_e32 v43, 1.0, v45
	v_rcp_f32_e32 v42, v42
	v_add_f32_e32 v45, 1.0, v46
	v_rcp_f32_e32 v43, v43
	v_rcp_f32_e32 v45, v45
	v_mov_b32_e32 v46, v38
	v_mov_b32_e32 v47, v40
	v_mov_b32_e32 v40, v39
	v_pk_mul_f32 v[42:43], v[46:47], v[42:43]
	v_mov_b32_e32 v47, v36
	v_pk_mul_f32 v[38:39], v[40:41], v[44:45]
	v_mov_b32_e32 v36, v35
	v_mov_b32_e32 v46, v34
	v_pk_mul_f32 v[34:35], v[36:37], v[38:39]
	v_pk_mul_f32 v[42:43], v[46:47], v[42:43]
	v_and_b32_sdwa v38, v35, v177 dst_sel:DWORD dst_unused:UNUSED_PAD src0_sel:WORD_1 src1_sel:DWORD
	v_and_b32_sdwa v39, v34, v177 dst_sel:DWORD dst_unused:UNUSED_PAD src0_sel:WORD_1 src1_sel:DWORD
	v_and_b32_sdwa v36, v43, v177 dst_sel:DWORD dst_unused:UNUSED_PAD src0_sel:WORD_1 src1_sel:DWORD
	v_and_b32_sdwa v37, v42, v177 dst_sel:DWORD dst_unused:UNUSED_PAD src0_sel:WORD_1 src1_sel:DWORD
	v_add3_u32 v35, v35, v38, s28
	v_add3_u32 v34, v34, v39, s28
	v_add3_u32 v37, v42, v37, s28
	v_add3_u32 v36, v43, v36, s28
	v_and_b32_e32 v35, 0xffff0000, v35
	v_and_b32_e32 v34, 0xffff0000, v34
	v_or_b32_sdwa v35, v35, v36 dst_sel:DWORD dst_unused:UNUSED_PAD src0_sel:DWORD src1_sel:WORD_1
	v_or_b32_sdwa v34, v34, v37 dst_sel:DWORD dst_unused:UNUSED_PAD src0_sel:DWORD src1_sel:WORD_1
	global_store_dwordx2 v[66:67], v[34:35], off offset:96
	v_mul_f32_e32 v35, 0xbfb8aa3b, v30
	v_exp_f32_e32 v36, v35
	v_mul_f32_e32 v35, 0xbfb8aa3b, v31
	v_mul_f32_e32 v38, 0xbfb8aa3b, v32
	v_exp_f32_e32 v37, v35
	v_exp_f32_e32 v39, v38
	v_mul_f32_e32 v38, 0xbfb8aa3b, v33
	v_exp_f32_e32 v40, v38
	v_add_f32_e32 v37, 1.0, v37
	v_add_f32_e32 v36, 1.0, v36
	v_rcp_f32_e32 v38, v37
	v_add_f32_e32 v37, 1.0, v39
	v_add_f32_e32 v39, 1.0, v40
	v_rcp_f32_e32 v36, v36
	v_rcp_f32_e32 v37, v37
	v_rcp_f32_e32 v39, v39
	v_mov_b32_e32 v40, v30
	v_mov_b32_e32 v41, v32
	v_mov_b32_e32 v32, v31
	v_pk_mul_f32 v[36:37], v[40:41], v[36:37]
	v_mov_b32_e32 v41, v28
	v_pk_mul_f32 v[30:31], v[32:33], v[38:39]
	v_mov_b32_e32 v28, v27
	v_mov_b32_e32 v40, v26
	v_pk_mul_f32 v[26:27], v[28:29], v[30:31]
	v_pk_mul_f32 v[36:37], v[40:41], v[36:37]
	v_and_b32_sdwa v30, v27, v177 dst_sel:DWORD dst_unused:UNUSED_PAD src0_sel:WORD_1 src1_sel:DWORD
	v_and_b32_sdwa v28, v37, v177 dst_sel:DWORD dst_unused:UNUSED_PAD src0_sel:WORD_1 src1_sel:DWORD
	v_and_b32_sdwa v31, v26, v177 dst_sel:DWORD dst_unused:UNUSED_PAD src0_sel:WORD_1 src1_sel:DWORD
	v_add3_u32 v27, v27, v30, s28
	v_and_b32_sdwa v29, v36, v177 dst_sel:DWORD dst_unused:UNUSED_PAD src0_sel:WORD_1 src1_sel:DWORD
	v_add3_u32 v28, v37, v28, s28
	v_add3_u32 v26, v26, v31, s28
	v_and_b32_e32 v27, 0xffff0000, v27
	v_add3_u32 v29, v36, v29, s28
	v_and_b32_e32 v26, 0xffff0000, v26
	v_or_b32_sdwa v27, v27, v28 dst_sel:DWORD dst_unused:UNUSED_PAD src0_sel:DWORD src1_sel:WORD_1
	v_mul_f32_e32 v28, 0xbfb8aa3b, v22
	v_or_b32_sdwa v26, v26, v29 dst_sel:DWORD dst_unused:UNUSED_PAD src0_sel:DWORD src1_sel:WORD_1
	v_exp_f32_e32 v28, v28
	v_mul_f32_e32 v29, 0xbfb8aa3b, v23
	v_or_b32_e32 v34, 48, v110
	v_exp_f32_e32 v29, v29
	v_mad_i64_i32 v[34:35], s[6:7], v34, s52, v[106:107]
	v_lshl_add_u64 v[34:35], v[34:35], 0, v[108:109]
	global_store_dwordx2 v[34:35], v[26:27], off
	v_add_f32_e32 v26, 1.0, v28
	v_mul_f32_e32 v28, 0xbfb8aa3b, v24
	v_add_f32_e32 v27, 1.0, v29
	v_exp_f32_e32 v29, v28
	v_mul_f32_e32 v28, 0xbfb8aa3b, v25
	v_exp_f32_e32 v30, v28
	v_rcp_f32_e32 v28, v27
	v_add_f32_e32 v27, 1.0, v29
	v_rcp_f32_e32 v26, v26
	v_add_f32_e32 v29, 1.0, v30
	v_rcp_f32_e32 v27, v27
	v_rcp_f32_e32 v29, v29
	v_mov_b32_e32 v30, v22
	v_mov_b32_e32 v31, v24
	v_mov_b32_e32 v24, v23
	v_pk_mul_f32 v[26:27], v[30:31], v[26:27]
	v_mov_b32_e32 v31, v20
	v_pk_mul_f32 v[22:23], v[24:25], v[28:29]
	v_mov_b32_e32 v20, v19
	v_mov_b32_e32 v30, v18
	v_pk_mul_f32 v[18:19], v[20:21], v[22:23]
	v_pk_mul_f32 v[26:27], v[30:31], v[26:27]
	v_and_b32_sdwa v22, v19, v177 dst_sel:DWORD dst_unused:UNUSED_PAD src0_sel:WORD_1 src1_sel:DWORD
	v_and_b32_sdwa v20, v27, v177 dst_sel:DWORD dst_unused:UNUSED_PAD src0_sel:WORD_1 src1_sel:DWORD
	v_and_b32_sdwa v23, v18, v177 dst_sel:DWORD dst_unused:UNUSED_PAD src0_sel:WORD_1 src1_sel:DWORD
	v_add3_u32 v19, v19, v22, s28
	v_and_b32_sdwa v21, v26, v177 dst_sel:DWORD dst_unused:UNUSED_PAD src0_sel:WORD_1 src1_sel:DWORD
	v_add3_u32 v20, v27, v20, s28
	v_add3_u32 v18, v18, v23, s28
	v_and_b32_e32 v19, 0xffff0000, v19
	v_add3_u32 v21, v26, v21, s28
	v_and_b32_e32 v18, 0xffff0000, v18
	v_or_b32_sdwa v19, v19, v20 dst_sel:DWORD dst_unused:UNUSED_PAD src0_sel:DWORD src1_sel:WORD_1
	v_mul_f32_e32 v20, 0xbfb8aa3b, v14
	v_or_b32_sdwa v18, v18, v21 dst_sel:DWORD dst_unused:UNUSED_PAD src0_sel:DWORD src1_sel:WORD_1
	v_exp_f32_e32 v20, v20
	v_mul_f32_e32 v21, 0xbfb8aa3b, v15
	v_exp_f32_e32 v21, v21
	global_store_dwordx2 v[34:35], v[18:19], off offset:32
	v_add_f32_e32 v18, 1.0, v20
	v_mul_f32_e32 v20, 0xbfb8aa3b, v16
	v_add_f32_e32 v19, 1.0, v21
	v_exp_f32_e32 v21, v20
	v_mul_f32_e32 v20, 0xbfb8aa3b, v17
	v_exp_f32_e32 v22, v20
	v_rcp_f32_e32 v20, v19
	v_add_f32_e32 v19, 1.0, v21
	v_rcp_f32_e32 v18, v18
	v_add_f32_e32 v21, 1.0, v22
	v_rcp_f32_e32 v19, v19
	v_rcp_f32_e32 v21, v21
	v_mov_b32_e32 v22, v14
	v_mov_b32_e32 v23, v16
	v_mov_b32_e32 v16, v15
	v_pk_mul_f32 v[18:19], v[22:23], v[18:19]
	v_mov_b32_e32 v23, v12
	v_pk_mul_f32 v[14:15], v[16:17], v[20:21]
	v_mov_b32_e32 v12, v11
	v_mov_b32_e32 v22, v10
	v_pk_mul_f32 v[10:11], v[12:13], v[14:15]
	v_pk_mul_f32 v[18:19], v[22:23], v[18:19]
	v_and_b32_sdwa v14, v11, v177 dst_sel:DWORD dst_unused:UNUSED_PAD src0_sel:WORD_1 src1_sel:DWORD
	v_and_b32_sdwa v12, v19, v177 dst_sel:DWORD dst_unused:UNUSED_PAD src0_sel:WORD_1 src1_sel:DWORD
	v_and_b32_sdwa v15, v10, v177 dst_sel:DWORD dst_unused:UNUSED_PAD src0_sel:WORD_1 src1_sel:DWORD
	v_add3_u32 v11, v11, v14, s28
	v_and_b32_sdwa v13, v18, v177 dst_sel:DWORD dst_unused:UNUSED_PAD src0_sel:WORD_1 src1_sel:DWORD
	v_add3_u32 v12, v19, v12, s28
	v_add3_u32 v10, v10, v15, s28
	v_and_b32_e32 v11, 0xffff0000, v11
	v_add3_u32 v13, v18, v13, s28
	v_and_b32_e32 v10, 0xffff0000, v10
	v_or_b32_sdwa v11, v11, v12 dst_sel:DWORD dst_unused:UNUSED_PAD src0_sel:DWORD src1_sel:WORD_1
	v_mul_f32_e32 v12, 0xbfb8aa3b, v6
	v_or_b32_sdwa v10, v10, v13 dst_sel:DWORD dst_unused:UNUSED_PAD src0_sel:DWORD src1_sel:WORD_1
	v_exp_f32_e32 v12, v12
	v_mul_f32_e32 v13, 0xbfb8aa3b, v7
	v_exp_f32_e32 v13, v13
	global_store_dwordx2 v[34:35], v[10:11], off offset:64
	v_add_f32_e32 v10, 1.0, v12
	v_mul_f32_e32 v12, 0xbfb8aa3b, v8
	v_add_f32_e32 v11, 1.0, v13
	v_exp_f32_e32 v13, v12
	v_mul_f32_e32 v12, 0xbfb8aa3b, v9
	v_exp_f32_e32 v14, v12
	v_rcp_f32_e32 v12, v11
	v_add_f32_e32 v11, 1.0, v13
	v_rcp_f32_e32 v10, v10
	v_add_f32_e32 v13, 1.0, v14
	v_rcp_f32_e32 v11, v11
	v_rcp_f32_e32 v13, v13
	v_mov_b32_e32 v14, v6
	v_mov_b32_e32 v15, v8
	v_mov_b32_e32 v8, v7
	v_pk_mul_f32 v[10:11], v[14:15], v[10:11]
	v_mov_b32_e32 v15, v4
	v_pk_mul_f32 v[6:7], v[8:9], v[12:13]
	v_mov_b32_e32 v4, v3
	v_mov_b32_e32 v14, v2
	v_pk_mul_f32 v[2:3], v[4:5], v[6:7]
	v_pk_mul_f32 v[10:11], v[14:15], v[10:11]
	v_and_b32_sdwa v6, v3, v177 dst_sel:DWORD dst_unused:UNUSED_PAD src0_sel:WORD_1 src1_sel:DWORD
	v_and_b32_sdwa v7, v2, v177 dst_sel:DWORD dst_unused:UNUSED_PAD src0_sel:WORD_1 src1_sel:DWORD
	v_and_b32_sdwa v4, v11, v177 dst_sel:DWORD dst_unused:UNUSED_PAD src0_sel:WORD_1 src1_sel:DWORD
	v_and_b32_sdwa v5, v10, v177 dst_sel:DWORD dst_unused:UNUSED_PAD src0_sel:WORD_1 src1_sel:DWORD
	v_add3_u32 v3, v3, v6, s28
	v_add3_u32 v2, v2, v7, s28
	v_add3_u32 v5, v10, v5, s28
	v_add3_u32 v4, v11, v4, s28
	v_and_b32_e32 v3, 0xffff0000, v3
	v_and_b32_e32 v2, 0xffff0000, v2
	s_add_i32 s20, s20, s11
	v_or_b32_sdwa v3, v3, v4 dst_sel:DWORD dst_unused:UNUSED_PAD src0_sel:DWORD src1_sel:WORD_1
	v_or_b32_sdwa v2, v2, v5 dst_sel:DWORD dst_unused:UNUSED_PAD src0_sel:DWORD src1_sel:WORD_1
	s_cmpk_gt_i32 s20, 0x5ff
	global_store_dwordx2 v[34:35], v[2:3], off offset:96
	s_cbranch_scc0 .LBB0_465

	.amdhsa_kernel _Z14fwd_megakernel1P
		.amdhsa_group_segment_fixed_size 147480
		.amdhsa_private_segment_fixed_size 0
		.amdhsa_kernarg_size 576
		.amdhsa_user_sgpr_count 2
		.amdhsa_user_sgpr_dispatch_ptr 0
		.amdhsa_user_sgpr_queue_ptr 0
		.amdhsa_user_sgpr_kernarg_segment_ptr 1
		.amdhsa_user_sgpr_dispatch_id 0
		.amdhsa_user_sgpr_kernarg_preload_length 0
		.amdhsa_user_sgpr_kernarg_preload_offset 0
		.amdhsa_user_sgpr_private_segment_size 0
		.amdhsa_uses_dynamic_stack 0
		.amdhsa_enable_private_segment 0
		.amdhsa_system_sgpr_workgroup_id_x 1
		.amdhsa_system_sgpr_workgroup_id_y 0
		.amdhsa_system_sgpr_workgroup_id_z 0
		.amdhsa_system_sgpr_workgroup_info 0
		.amdhsa_system_vgpr_workitem_id 2
		.amdhsa_next_free_vgpr 256
		.amdhsa_next_free_sgpr 102
		.amdhsa_accum_offset 256
		.amdhsa_reserve_vcc 1
		.amdhsa_float_round_mode_32 0
		.amdhsa_float_round_mode_16_64 0
		.amdhsa_float_denorm_mode_32 3
		.amdhsa_float_denorm_mode_16_64 3
		.amdhsa_dx10_clamp 1
		.amdhsa_ieee_mode 1
		.amdhsa_fp16_overflow 0
		.amdhsa_tg_split 0
		.amdhsa_exception_fp_ieee_invalid_op 0
		.amdhsa_exception_fp_denorm_src 0
		.amdhsa_exception_fp_ieee_div_zero 0
		.amdhsa_exception_fp_ieee_overflow 0
		.amdhsa_exception_fp_ieee_underflow 0
		.amdhsa_exception_fp_ieee_inexact 0
		.amdhsa_exception_int_div_zero 0
	.end_amdhsa_kernel

amdhsa.kernels:
  - .agpr_count:     0
    .args:
      - .offset:         0
        .size:           320
        .value_kind:     by_value
      - .offset:         320
        .size:           4
        .value_kind:     hidden_block_count_x
      - .offset:         324
        .size:           4
        .value_kind:     hidden_block_count_y
      - .offset:         328
        .size:           4
        .value_kind:     hidden_block_count_z
      - .offset:         332
        .size:           2
        .value_kind:     hidden_group_size_x
      - .offset:         334
        .size:           2
        .value_kind:     hidden_group_size_y
      - .offset:         336
        .size:           2
        .value_kind:     hidden_group_size_z
      - .offset:         338
        .size:           2
        .value_kind:     hidden_remainder_x
      - .offset:         340
        .size:           2
        .value_kind:     hidden_remainder_y
      - .offset:         342
        .size:           2
        .value_kind:     hidden_remainder_z
      - .offset:         360
        .size:           8
        .value_kind:     hidden_global_offset_x
      - .offset:         368
        .size:           8
        .value_kind:     hidden_global_offset_y
      - .offset:         376
        .size:           8
        .value_kind:     hidden_global_offset_z
      - .offset:         384
        .size:           2
        .value_kind:     hidden_grid_dims
      - .offset:         408
        .size:           8
        .value_kind:     hidden_multigrid_sync_arg
    .group_segment_fixed_size: 147480
    .kernarg_segment_align: 8
    .kernarg_segment_size: 576
    .language:       OpenCL C
    .language_version:
      - 2
      - 0
    .max_flat_workgroup_size: 512
    .name:           _Z14fwd_megakernel1P
    .private_segment_fixed_size: 0
    .sgpr_count:     108
    .sgpr_spill_count: 199
    .symbol:         _Z14fwd_megakernel1P.kd
    .uniform_work_group_size: 1
    .uses_dynamic_stack: false
    .vgpr_count:     256
    .vgpr_spill_count: 0
    .wavefront_size: 64
